# early-conversion jobs batched two at a time per wave (32 dwordx4 loads in flight), same work as before
# baseline (speedup 1.0000x reference)
; __device__ __forceinline__ unsigned pk_bf16(float lo, float hi) { unsigned r; asm volatile("v_cvt_pk_bf16_f32 %0, %1, %2" : "=v"(r) : "v"(lo), "v"(hi)); return r; }
; #define WT_LOAD() do { _Pragma("unroll") for (int i = 0; i < 16; ++i) rg[i] = sp ? sp[(size_t)(k0 + kq + i * 8) * ld] : 0.f; } while (0)
; __device__ __forceinline__ void phase_weights(int wv, const Params& p, int l, LAS unsigned char* lds, int first, int stride) {
;     ...
;     if (ti < 1536) { WT_DECODE(ti); WT_LOAD(); }
;     while (ti < 1536) {
;         bf16_t* cdst = dst + (size_t)n0 * K + k0; const int cK = K;
;         __syncthreads();
; #pragma unroll
;         for (int i = 0; i < 16; ++i) tile[(kq + i * 8) * 65 + nl] = rg[i];
;         ti += stride;
;         if (ti < 1536) { WT_DECODE(ti); WT_LOAD(); }
;         __syncthreads();
;         { const int nn = tid >> 3, ks = tid & 7; float v[16];
; #pragma unroll
;             for (int j = 0; j < 16; ++j) v[j] = tile[(ks * 16 + j) * 65 + nn];
;             u32x4 w0, w1; w0.x = pk_bf16(v[0], v[1]); w0.y = pk_bf16(v[2], v[3]); w0.z = pk_bf16(v[4], v[5]); w0.w = pk_bf16(v[6], v[7]);
;             w1.x = pk_bf16(v[8], v[9]); w1.y = pk_bf16(v[10], v[11]); w1.z = pk_bf16(v[12], v[13]); w1.w = pk_bf16(v[14], v[15]);
;             bf16_t* o = cdst + (size_t)nn * cK + ks * 16; *(u32x4*)o = w0; *(u32x4*)(o + 8) = w1; }
.LBB0_1505:
	v_readlane_b32 s24, v255, 3
	s_cmpk_lt_u32 s24, 160
	s_cbranch_scc1 .Lew_end_b
	s_cmpk_lg_u32 s44, 0x100
	s_cbranch_scc1 .Lew_end_b
	s_load_dwordx2 s[8:9], s[90:91], 0x88
	s_load_dwordx2 s[10:11], s[90:91], 0x90
	s_load_dwordx2 s[12:13], s[90:91], 0xa8
	v_mbcnt_lo_u32_b32 v2, -1, 0
	v_mbcnt_hi_u32_b32 v2, -1, v2
	v_and_b32_e32 v3, 15, v2
	v_lshrrev_b32_e32 v6, 5, v2
	v_lshlrev_b32_e32 v7, 4, v3
	v_mul_u32_u24_e32 v8, 0x2c000, v6
	v_add_u32_e32 v12, v7, v8
	v_add_u32_e32 v12, 0xb00000, v12
	v_mov_b32_e32 v13, 0
	v_and_b32_e32 v8, 16, v2
	v_cmp_ne_u32_e32 vcc, 0, v8
	s_waitcnt lgkmcnt(0)
	v_mov_b32_e32 v4, s8
	v_mov_b32_e32 v5, s9
	v_mov_b32_e32 v8, s10
	v_mov_b32_e32 v9, s11
	s_nop 1
	v_cndmask_b32_e32 v4, v4, v8, vcc
	v_cndmask_b32_e32 v5, v5, v9, vcc
	v_lshl_add_u64 v[4:5], v[4:5], 0, v[12:13]
	v_and_b32_e32 v8, 1, v3
	v_lshlrev_b32_e32 v10, 7, v8
	v_bfe_u32 v8, v3, 1, 2
	v_lshl_add_u32 v10, v8, 2, v10
	v_lshrrev_b32_e32 v8, 3, v3
	v_lshl_add_u32 v10, v8, 5, v10
	v_bfe_u32 v8, v2, 4, 1
	v_lshl_add_u32 v10, v8, 4, v10
	v_add_u32_e32 v10, 2, v10
	v_lshlrev_b32_e32 v10, 11, v10
	v_lshl_add_u32 v10, v6, 5, v10
	s_add_u32 s12, s12, 0xb34c000
	s_addc_u32 s13, s13, 0
	v_readlane_b32 s24, v255, 7
	s_lshr_b32 s24, s24, 6
	v_readlane_b32 s3, v255, 3
	s_sub_i32 s3, s3, 160
	s_lshl_b32 s3, s3, 3
	s_add_i32 s3, s3, s24
	s_lshr_b32 s6, s3, 5
	s_and_b32 s7, s3, 31
	s_lshr_b32 s15, s6, 1
	s_and_b32 s6, s6, 1
	s_lshl_b32 s26, s15, 9
	s_lshl_b32 s27, s6, 8
	s_add_i32 s26, s26, s27
	s_mul_i32 s27, s7, 0x58000
	s_add_i32 s22, s26, s27
	s_mov_b32 s23, 0
	s_lshl_b32 s26, s15, 19
	s_lshl_b32 s27, s6, 17
	s_add_i32 s26, s26, s27
	s_lshl_b32 s27, s7, 6
	s_add_i32 s26, s26, s27
	s_add_u32 s30, s12, s26
	s_addc_u32 s31, s13, 0
	v_lshl_add_u64 v[6:7], s[22:23], 0, v[4:5]
	global_load_dwordx4 v[20:23], v[6:7], off
	s_add_u32 s22, s22, 0x2c00
	v_lshl_add_u64 v[8:9], s[22:23], 0, v[4:5]
	global_load_dwordx4 v[24:27], v[8:9], off
	s_add_u32 s22, s22, 0x2c00
	v_lshl_add_u64 v[6:7], s[22:23], 0, v[4:5]
	global_load_dwordx4 v[28:31], v[6:7], off
	s_add_u32 s22, s22, 0x2c00
	v_lshl_add_u64 v[8:9], s[22:23], 0, v[4:5]
	global_load_dwordx4 v[32:35], v[8:9], off
	s_add_u32 s22, s22, 0x2c00
	v_lshl_add_u64 v[6:7], s[22:23], 0, v[4:5]
	global_load_dwordx4 v[36:39], v[6:7], off
	s_add_u32 s22, s22, 0x2c00
	v_lshl_add_u64 v[8:9], s[22:23], 0, v[4:5]
	global_load_dwordx4 v[40:43], v[8:9], off
	s_add_u32 s22, s22, 0x2c00
	v_lshl_add_u64 v[6:7], s[22:23], 0, v[4:5]
	global_load_dwordx4 v[44:47], v[6:7], off
	s_add_u32 s22, s22, 0x2c00
	v_lshl_add_u64 v[8:9], s[22:23], 0, v[4:5]
	global_load_dwordx4 v[48:51], v[8:9], off
	s_add_u32 s22, s22, 0x2c00
	v_lshl_add_u64 v[6:7], s[22:23], 0, v[4:5]
	global_load_dwordx4 v[52:55], v[6:7], off
	s_add_u32 s22, s22, 0x2c00
	v_lshl_add_u64 v[8:9], s[22:23], 0, v[4:5]
	global_load_dwordx4 v[56:59], v[8:9], off
	s_add_u32 s22, s22, 0x2c00
	v_lshl_add_u64 v[6:7], s[22:23], 0, v[4:5]
	global_load_dwordx4 v[60:63], v[6:7], off
	s_add_u32 s22, s22, 0x2c00
	v_lshl_add_u64 v[8:9], s[22:23], 0, v[4:5]
	global_load_dwordx4 v[64:67], v[8:9], off
	s_add_u32 s22, s22, 0x2c00
	v_lshl_add_u64 v[6:7], s[22:23], 0, v[4:5]
	global_load_dwordx4 v[68:71], v[6:7], off
	s_add_u32 s22, s22, 0x2c00
	v_lshl_add_u64 v[8:9], s[22:23], 0, v[4:5]
	global_load_dwordx4 v[72:75], v[8:9], off
	s_add_u32 s22, s22, 0x2c00
	v_lshl_add_u64 v[6:7], s[22:23], 0, v[4:5]
	global_load_dwordx4 v[76:79], v[6:7], off
	s_add_u32 s22, s22, 0x2c00
	v_lshl_add_u64 v[8:9], s[22:23], 0, v[4:5]
	global_load_dwordx4 v[80:83], v[8:9], off
	s_add_u32 s22, s22, 0x2c00
	s_cmpk_lt_u32 s3, 0x280
	s_cbranch_scc0 .Lew_hi
	s_add_i32 s14, s3, 0x300
	s_lshr_b32 s6, s14, 5
	s_and_b32 s7, s14, 31
	s_lshr_b32 s15, s6, 1
	s_and_b32 s6, s6, 1
	s_lshl_b32 s26, s15, 9
	s_lshl_b32 s27, s6, 8
	s_add_i32 s26, s26, s27
	s_mul_i32 s27, s7, 0x58000
	s_add_i32 s18, s26, s27
	s_mov_b32 s19, 0
	s_lshl_b32 s26, s15, 19
	s_lshl_b32 s27, s6, 17
	s_add_i32 s26, s26, s27
	s_lshl_b32 s27, s7, 6
	s_add_i32 s26, s26, s27
	s_add_u32 s20, s12, s26
	s_addc_u32 s21, s13, 0
	v_lshl_add_u64 v[6:7], s[18:19], 0, v[4:5]
	global_load_dwordx4 v[116:119], v[6:7], off
	s_add_u32 s18, s18, 0x2c00
	v_lshl_add_u64 v[8:9], s[18:19], 0, v[4:5]
	global_load_dwordx4 v[120:123], v[8:9], off
	s_add_u32 s18, s18, 0x2c00
	v_lshl_add_u64 v[6:7], s[18:19], 0, v[4:5]
	global_load_dwordx4 v[124:127], v[6:7], off
	s_add_u32 s18, s18, 0x2c00
	v_lshl_add_u64 v[8:9], s[18:19], 0, v[4:5]
	global_load_dwordx4 v[128:131], v[8:9], off
	s_add_u32 s18, s18, 0x2c00
	v_lshl_add_u64 v[6:7], s[18:19], 0, v[4:5]
	global_load_dwordx4 v[132:135], v[6:7], off
	s_add_u32 s18, s18, 0x2c00
	v_lshl_add_u64 v[8:9], s[18:19], 0, v[4:5]
	global_load_dwordx4 v[136:139], v[8:9], off
	s_add_u32 s18, s18, 0x2c00
	v_lshl_add_u64 v[6:7], s[18:19], 0, v[4:5]
	global_load_dwordx4 v[140:143], v[6:7], off
	s_add_u32 s18, s18, 0x2c00
	v_lshl_add_u64 v[8:9], s[18:19], 0, v[4:5]
	global_load_dwordx4 v[144:147], v[8:9], off
	s_add_u32 s18, s18, 0x2c00
	v_lshl_add_u64 v[6:7], s[18:19], 0, v[4:5]
	global_load_dwordx4 v[148:151], v[6:7], off
	s_add_u32 s18, s18, 0x2c00
	v_lshl_add_u64 v[8:9], s[18:19], 0, v[4:5]
	global_load_dwordx4 v[152:155], v[8:9], off
	s_add_u32 s18, s18, 0x2c00
	v_lshl_add_u64 v[6:7], s[18:19], 0, v[4:5]
	global_load_dwordx4 v[156:159], v[6:7], off
	s_add_u32 s18, s18, 0x2c00
	v_lshl_add_u64 v[8:9], s[18:19], 0, v[4:5]
	global_load_dwordx4 v[160:163], v[8:9], off
	s_add_u32 s18, s18, 0x2c00
	v_lshl_add_u64 v[6:7], s[18:19], 0, v[4:5]
	global_load_dwordx4 v[164:167], v[6:7], off
	s_add_u32 s18, s18, 0x2c00
	v_lshl_add_u64 v[8:9], s[18:19], 0, v[4:5]
	global_load_dwordx4 v[168:171], v[8:9], off
	s_add_u32 s18, s18, 0x2c00
	v_lshl_add_u64 v[6:7], s[18:19], 0, v[4:5]
	global_load_dwordx4 v[172:175], v[6:7], off
	s_add_u32 s18, s18, 0x2c00
	v_lshl_add_u64 v[8:9], s[18:19], 0, v[4:5]
	global_load_dwordx4 v[176:179], v[8:9], off
	s_add_u32 s18, s18, 0x2c00
	s_waitcnt vmcnt(16)
; __device__ __forceinline__ unsigned pk_bf16(float lo, float hi) { unsigned r; asm volatile("v_cvt_pk_bf16_f32 %0, %1, %2" : "=v"(r) : "v"(lo), "v"(hi)); return r; }
; #define WT_LOAD() do { _Pragma("unroll") for (int i = 0; i < 16; ++i) rg[i] = sp ? sp[(size_t)(k0 + kq + i * 8) * ld] : 0.f; } while (0)
; __device__ __forceinline__ void phase_weights(int wv, const Params& p, int l, LAS unsigned char* lds, int first, int stride) {
;     ...
;     if (ti < 1536) { WT_DECODE(ti); WT_LOAD(); }
;     while (ti < 1536) {
;         bf16_t* cdst = dst + (size_t)n0 * K + k0; const int cK = K;
;         __syncthreads();
; #pragma unroll
;         for (int i = 0; i < 16; ++i) tile[(kq + i * 8) * 65 + nl] = rg[i];
;         ti += stride;
;         if (ti < 1536) { WT_DECODE(ti); WT_LOAD(); }
;         __syncthreads();
;         { const int nn = tid >> 3, ks = tid & 7; float v[16];
; #pragma unroll
;             for (int j = 0; j < 16; ++j) v[j] = tile[(ks * 16 + j) * 65 + nn];
;             u32x4 w0, w1; w0.x = pk_bf16(v[0], v[1]); w0.y = pk_bf16(v[2], v[3]); w0.z = pk_bf16(v[4], v[5]); w0.w = pk_bf16(v[6], v[7]);
;             w1.x = pk_bf16(v[8], v[9]); w1.y = pk_bf16(v[10], v[11]); w1.z = pk_bf16(v[12], v[13]); w1.w = pk_bf16(v[14], v[15]);
;             bf16_t* o = cdst + (size_t)nn * cK + ks * 16; *(u32x4*)o = w0; *(u32x4*)(o + 8) = w1; }
	v_cvt_pk_bf16_f32 v84, v20, v24
	v_cvt_pk_bf16_f32 v85, v28, v32
	v_cvt_pk_bf16_f32 v86, v36, v40
	v_cvt_pk_bf16_f32 v87, v44, v48
	v_cvt_pk_bf16_f32 v88, v52, v56
	v_cvt_pk_bf16_f32 v89, v60, v64
	v_cvt_pk_bf16_f32 v90, v68, v72
	v_cvt_pk_bf16_f32 v91, v76, v80
	v_cvt_pk_bf16_f32 v92, v21, v25
	v_cvt_pk_bf16_f32 v93, v29, v33
	v_cvt_pk_bf16_f32 v94, v37, v41
	v_cvt_pk_bf16_f32 v95, v45, v49
	v_cvt_pk_bf16_f32 v96, v53, v57
	v_cvt_pk_bf16_f32 v97, v61, v65
	v_cvt_pk_bf16_f32 v98, v69, v73
	v_cvt_pk_bf16_f32 v99, v77, v81
	v_cvt_pk_bf16_f32 v100, v22, v26
	v_cvt_pk_bf16_f32 v101, v30, v34
	v_cvt_pk_bf16_f32 v102, v38, v42
	v_cvt_pk_bf16_f32 v103, v46, v50
	v_cvt_pk_bf16_f32 v104, v54, v58
	v_cvt_pk_bf16_f32 v105, v62, v66
	v_cvt_pk_bf16_f32 v106, v70, v74
	v_cvt_pk_bf16_f32 v107, v78, v82
	v_cvt_pk_bf16_f32 v108, v23, v27
	v_cvt_pk_bf16_f32 v109, v31, v35
	v_cvt_pk_bf16_f32 v110, v39, v43
	v_cvt_pk_bf16_f32 v111, v47, v51
	v_cvt_pk_bf16_f32 v112, v55, v59
	v_cvt_pk_bf16_f32 v113, v63, v67
	v_cvt_pk_bf16_f32 v114, v71, v75
	v_cvt_pk_bf16_f32 v115, v79, v83
	global_store_dwordx4 v10, v[84:87], s[30:31] offset:-4096
	global_store_dwordx4 v10, v[88:91], s[30:31] offset:-4080
	global_store_dwordx4 v10, v[92:95], s[30:31] offset:-2048
	global_store_dwordx4 v10, v[96:99], s[30:31] offset:-2032
	global_store_dwordx4 v10, v[100:103], s[30:31]
	global_store_dwordx4 v10, v[104:107], s[30:31] offset:16
	global_store_dwordx4 v10, v[108:111], s[30:31] offset:2048
	global_store_dwordx4 v10, v[112:115], s[30:31] offset:2064
	s_waitcnt vmcnt(0)
	v_cvt_pk_bf16_f32 v84, v116, v120
	v_cvt_pk_bf16_f32 v85, v124, v128
	v_cvt_pk_bf16_f32 v86, v132, v136
	v_cvt_pk_bf16_f32 v87, v140, v144
	v_cvt_pk_bf16_f32 v88, v148, v152
	v_cvt_pk_bf16_f32 v89, v156, v160
	v_cvt_pk_bf16_f32 v90, v164, v168
	v_cvt_pk_bf16_f32 v91, v172, v176
	v_cvt_pk_bf16_f32 v92, v117, v121
	v_cvt_pk_bf16_f32 v93, v125, v129
	v_cvt_pk_bf16_f32 v94, v133, v137
	v_cvt_pk_bf16_f32 v95, v141, v145
	v_cvt_pk_bf16_f32 v96, v149, v153
	v_cvt_pk_bf16_f32 v97, v157, v161
	v_cvt_pk_bf16_f32 v98, v165, v169
	v_cvt_pk_bf16_f32 v99, v173, v177
	v_cvt_pk_bf16_f32 v100, v118, v122
	v_cvt_pk_bf16_f32 v101, v126, v130
	v_cvt_pk_bf16_f32 v102, v134, v138
	v_cvt_pk_bf16_f32 v103, v142, v146
	v_cvt_pk_bf16_f32 v104, v150, v154
	v_cvt_pk_bf16_f32 v105, v158, v162
	v_cvt_pk_bf16_f32 v106, v166, v170
	v_cvt_pk_bf16_f32 v107, v174, v178
	v_cvt_pk_bf16_f32 v108, v119, v123
	v_cvt_pk_bf16_f32 v109, v127, v131
	v_cvt_pk_bf16_f32 v110, v135, v139
	v_cvt_pk_bf16_f32 v111, v143, v147
	v_cvt_pk_bf16_f32 v112, v151, v155
	v_cvt_pk_bf16_f32 v113, v159, v163
	v_cvt_pk_bf16_f32 v114, v167, v171
	v_cvt_pk_bf16_f32 v115, v175, v179
	global_store_dwordx4 v10, v[84:87], s[20:21] offset:-4096
	global_store_dwordx4 v10, v[88:91], s[20:21] offset:-4080
	global_store_dwordx4 v10, v[92:95], s[20:21] offset:-2048
	global_store_dwordx4 v10, v[96:99], s[20:21] offset:-2032
	global_store_dwordx4 v10, v[100:103], s[20:21]
	global_store_dwordx4 v10, v[104:107], s[20:21] offset:16
	global_store_dwordx4 v10, v[108:111], s[20:21] offset:2048
	global_store_dwordx4 v10, v[112:115], s[20:21] offset:2064
	s_branch .Lew_end_b
.Lew_hi:
	s_sub_i32 s14, s3, 0x280
	s_load_dwordx2 s[10:11], s[90:91], 0x80
	v_lshrrev_b32_e32 v6, 4, v2
	v_lshlrev_b32_e32 v12, 4, v3
	v_lshl_add_u32 v12, v6, 16, v12
	v_add_u32_e32 v12, 0x400000, v12
	v_mov_b32_e32 v13, 0
	v_lshlrev_b32_e32 v11, 13, v3
	v_lshl_add_u32 v11, v6, 5, v11
	v_add_u32_e32 v11, 0x1000, v11
	s_waitcnt lgkmcnt(0)
	v_mov_b32_e32 v14, s10
	v_mov_b32_e32 v15, s11
	v_lshl_add_u64 v[14:15], v[14:15], 0, v[12:13]
	s_add_u32 s8, s12, 0xb00000
	s_addc_u32 s9, s13, 0
	s_lshr_b32 s6, s14, 4
	s_and_b32 s7, s14, 15
	s_lshl_b32 s18, s7, 18
	s_lshl_b32 s26, s6, 8
	s_add_i32 s18, s18, s26
	s_mov_b32 s19, 0
	s_lshl_b32 s26, s6, 17
	s_lshl_b32 s27, s7, 7
	s_add_i32 s26, s26, s27
	s_add_u32 s20, s8, s26
	s_addc_u32 s21, s9, 0
	v_lshl_add_u64 v[6:7], s[18:19], 0, v[14:15]
	global_load_dwordx4 v[116:119], v[6:7], off
	s_add_u32 s18, s18, 0x1000
	v_lshl_add_u64 v[8:9], s[18:19], 0, v[14:15]
	global_load_dwordx4 v[120:123], v[8:9], off
	s_add_u32 s18, s18, 0x1000
	v_lshl_add_u64 v[6:7], s[18:19], 0, v[14:15]
	global_load_dwordx4 v[124:127], v[6:7], off
	s_add_u32 s18, s18, 0x1000
	v_lshl_add_u64 v[8:9], s[18:19], 0, v[14:15]
	global_load_dwordx4 v[128:131], v[8:9], off
	s_add_u32 s18, s18, 0x1000
	v_lshl_add_u64 v[6:7], s[18:19], 0, v[14:15]
	global_load_dwordx4 v[132:135], v[6:7], off
	s_add_u32 s18, s18, 0x1000
	v_lshl_add_u64 v[8:9], s[18:19], 0, v[14:15]
	global_load_dwordx4 v[136:139], v[8:9], off
	s_add_u32 s18, s18, 0x1000
	v_lshl_add_u64 v[6:7], s[18:19], 0, v[14:15]
	global_load_dwordx4 v[140:143], v[6:7], off
	s_add_u32 s18, s18, 0x1000
	v_lshl_add_u64 v[8:9], s[18:19], 0, v[14:15]
	global_load_dwordx4 v[144:147], v[8:9], off
	s_add_u32 s18, s18, 0x1000
	v_lshl_add_u64 v[6:7], s[18:19], 0, v[14:15]
	global_load_dwordx4 v[148:151], v[6:7], off
	s_add_u32 s18, s18, 0x1000
	v_lshl_add_u64 v[8:9], s[18:19], 0, v[14:15]
	global_load_dwordx4 v[152:155], v[8:9], off
	s_add_u32 s18, s18, 0x1000
	v_lshl_add_u64 v[6:7], s[18:19], 0, v[14:15]
	global_load_dwordx4 v[156:159], v[6:7], off
	s_add_u32 s18, s18, 0x1000
	v_lshl_add_u64 v[8:9], s[18:19], 0, v[14:15]
	global_load_dwordx4 v[160:163], v[8:9], off
	s_add_u32 s18, s18, 0x1000
	v_lshl_add_u64 v[6:7], s[18:19], 0, v[14:15]
	global_load_dwordx4 v[164:167], v[6:7], off
	s_add_u32 s18, s18, 0x1000
	v_lshl_add_u64 v[8:9], s[18:19], 0, v[14:15]
	global_load_dwordx4 v[168:171], v[8:9], off
	s_add_u32 s18, s18, 0x1000
	v_lshl_add_u64 v[6:7], s[18:19], 0, v[14:15]
	global_load_dwordx4 v[172:175], v[6:7], off
	s_add_u32 s18, s18, 0x1000
	v_lshl_add_u64 v[8:9], s[18:19], 0, v[14:15]
	global_load_dwordx4 v[176:179], v[8:9], off
	s_add_u32 s18, s18, 0x1000
	s_waitcnt vmcnt(16)
; __device__ __forceinline__ unsigned pk_bf16(float lo, float hi) { unsigned r; asm volatile("v_cvt_pk_bf16_f32 %0, %1, %2" : "=v"(r) : "v"(lo), "v"(hi)); return r; }
; #define WT_LOAD() do { _Pragma("unroll") for (int i = 0; i < 16; ++i) rg[i] = sp ? sp[(size_t)(k0 + kq + i * 8) * ld] : 0.f; } while (0)
; __device__ __forceinline__ void phase_weights(int wv, const Params& p, int l, LAS unsigned char* lds, int first, int stride) {
;     ...
;     if (ti < 1536) { WT_DECODE(ti); WT_LOAD(); }
;     while (ti < 1536) {
;         bf16_t* cdst = dst + (size_t)n0 * K + k0; const int cK = K;
;         __syncthreads();
; #pragma unroll
;         for (int i = 0; i < 16; ++i) tile[(kq + i * 8) * 65 + nl] = rg[i];
;         ti += stride;
;         if (ti < 1536) { WT_DECODE(ti); WT_LOAD(); }
;         __syncthreads();
;         { const int nn = tid >> 3, ks = tid & 7; float v[16];
; #pragma unroll
;             for (int j = 0; j < 16; ++j) v[j] = tile[(ks * 16 + j) * 65 + nn];
;             u32x4 w0, w1; w0.x = pk_bf16(v[0], v[1]); w0.y = pk_bf16(v[2], v[3]); w0.z = pk_bf16(v[4], v[5]); w0.w = pk_bf16(v[6], v[7]);
;             w1.x = pk_bf16(v[8], v[9]); w1.y = pk_bf16(v[10], v[11]); w1.z = pk_bf16(v[12], v[13]); w1.w = pk_bf16(v[14], v[15]);
;             bf16_t* o = cdst + (size_t)nn * cK + ks * 16; *(u32x4*)o = w0; *(u32x4*)(o + 8) = w1; }
	v_cvt_pk_bf16_f32 v84, v20, v24
	v_cvt_pk_bf16_f32 v85, v28, v32
	v_cvt_pk_bf16_f32 v86, v36, v40
	v_cvt_pk_bf16_f32 v87, v44, v48
	v_cvt_pk_bf16_f32 v88, v52, v56
	v_cvt_pk_bf16_f32 v89, v60, v64
	v_cvt_pk_bf16_f32 v90, v68, v72
	v_cvt_pk_bf16_f32 v91, v76, v80
	v_cvt_pk_bf16_f32 v92, v21, v25
	v_cvt_pk_bf16_f32 v93, v29, v33
	v_cvt_pk_bf16_f32 v94, v37, v41
	v_cvt_pk_bf16_f32 v95, v45, v49
	v_cvt_pk_bf16_f32 v96, v53, v57
	v_cvt_pk_bf16_f32 v97, v61, v65
	v_cvt_pk_bf16_f32 v98, v69, v73
	v_cvt_pk_bf16_f32 v99, v77, v81
	v_cvt_pk_bf16_f32 v100, v22, v26
	v_cvt_pk_bf16_f32 v101, v30, v34
	v_cvt_pk_bf16_f32 v102, v38, v42
	v_cvt_pk_bf16_f32 v103, v46, v50
	v_cvt_pk_bf16_f32 v104, v54, v58
	v_cvt_pk_bf16_f32 v105, v62, v66
	v_cvt_pk_bf16_f32 v106, v70, v74
	v_cvt_pk_bf16_f32 v107, v78, v82
	v_cvt_pk_bf16_f32 v108, v23, v27
	v_cvt_pk_bf16_f32 v109, v31, v35
	v_cvt_pk_bf16_f32 v110, v39, v43
	v_cvt_pk_bf16_f32 v111, v47, v51
	v_cvt_pk_bf16_f32 v112, v55, v59
	v_cvt_pk_bf16_f32 v113, v63, v67
	v_cvt_pk_bf16_f32 v114, v71, v75
	v_cvt_pk_bf16_f32 v115, v79, v83
	global_store_dwordx4 v10, v[84:87], s[30:31] offset:-4096
	global_store_dwordx4 v10, v[88:91], s[30:31] offset:-4080
	global_store_dwordx4 v10, v[92:95], s[30:31] offset:-2048
	global_store_dwordx4 v10, v[96:99], s[30:31] offset:-2032
	global_store_dwordx4 v10, v[100:103], s[30:31]
	global_store_dwordx4 v10, v[104:107], s[30:31] offset:16
	global_store_dwordx4 v10, v[108:111], s[30:31] offset:2048
	global_store_dwordx4 v10, v[112:115], s[30:31] offset:2064
	s_addk_i32 s14, 0x80
	s_lshr_b32 s6, s14, 4
	s_and_b32 s7, s14, 15
	s_lshl_b32 s22, s7, 18
	s_lshl_b32 s26, s6, 8
	s_add_i32 s22, s22, s26
	s_mov_b32 s23, 0
	s_lshl_b32 s26, s6, 17
	s_lshl_b32 s27, s7, 7
	s_add_i32 s26, s26, s27
	s_add_u32 s30, s8, s26
	s_addc_u32 s31, s9, 0
	v_lshl_add_u64 v[6:7], s[22:23], 0, v[14:15]
	global_load_dwordx4 v[20:23], v[6:7], off
	s_add_u32 s22, s22, 0x1000
	v_lshl_add_u64 v[8:9], s[22:23], 0, v[14:15]
	global_load_dwordx4 v[24:27], v[8:9], off
	s_add_u32 s22, s22, 0x1000
	v_lshl_add_u64 v[6:7], s[22:23], 0, v[14:15]
	global_load_dwordx4 v[28:31], v[6:7], off
	s_add_u32 s22, s22, 0x1000
	v_lshl_add_u64 v[8:9], s[22:23], 0, v[14:15]
	global_load_dwordx4 v[32:35], v[8:9], off
	s_add_u32 s22, s22, 0x1000
	v_lshl_add_u64 v[6:7], s[22:23], 0, v[14:15]
	global_load_dwordx4 v[36:39], v[6:7], off
	s_add_u32 s22, s22, 0x1000
	v_lshl_add_u64 v[8:9], s[22:23], 0, v[14:15]
	global_load_dwordx4 v[40:43], v[8:9], off
	s_add_u32 s22, s22, 0x1000
	v_lshl_add_u64 v[6:7], s[22:23], 0, v[14:15]
	global_load_dwordx4 v[44:47], v[6:7], off
	s_add_u32 s22, s22, 0x1000
	v_lshl_add_u64 v[8:9], s[22:23], 0, v[14:15]
	global_load_dwordx4 v[48:51], v[8:9], off
	s_add_u32 s22, s22, 0x1000
	v_lshl_add_u64 v[6:7], s[22:23], 0, v[14:15]
	global_load_dwordx4 v[52:55], v[6:7], off
	s_add_u32 s22, s22, 0x1000
	v_lshl_add_u64 v[8:9], s[22:23], 0, v[14:15]
	global_load_dwordx4 v[56:59], v[8:9], off
	s_add_u32 s22, s22, 0x1000
	v_lshl_add_u64 v[6:7], s[22:23], 0, v[14:15]
	global_load_dwordx4 v[60:63], v[6:7], off
	s_add_u32 s22, s22, 0x1000
	v_lshl_add_u64 v[8:9], s[22:23], 0, v[14:15]
	global_load_dwordx4 v[64:67], v[8:9], off
	s_add_u32 s22, s22, 0x1000
	v_lshl_add_u64 v[6:7], s[22:23], 0, v[14:15]
	global_load_dwordx4 v[68:71], v[6:7], off
	s_add_u32 s22, s22, 0x1000
	v_lshl_add_u64 v[8:9], s[22:23], 0, v[14:15]
	global_load_dwordx4 v[72:75], v[8:9], off
	s_add_u32 s22, s22, 0x1000
	v_lshl_add_u64 v[6:7], s[22:23], 0, v[14:15]
	global_load_dwordx4 v[76:79], v[6:7], off
	s_add_u32 s22, s22, 0x1000
	v_lshl_add_u64 v[8:9], s[22:23], 0, v[14:15]
	global_load_dwordx4 v[80:83], v[8:9], off
	s_add_u32 s22, s22, 0x1000
	s_waitcnt vmcnt(16)
	v_cvt_pk_bf16_f32 v84, v116, v120
	v_cvt_pk_bf16_f32 v85, v124, v128
	v_cvt_pk_bf16_f32 v86, v132, v136
	v_cvt_pk_bf16_f32 v87, v140, v144
	v_cvt_pk_bf16_f32 v88, v148, v152
	v_cvt_pk_bf16_f32 v89, v156, v160
	v_cvt_pk_bf16_f32 v90, v164, v168
	v_cvt_pk_bf16_f32 v91, v172, v176
	v_cvt_pk_bf16_f32 v92, v117, v121
	v_cvt_pk_bf16_f32 v93, v125, v129
	v_cvt_pk_bf16_f32 v94, v133, v137
	v_cvt_pk_bf16_f32 v95, v141, v145
	v_cvt_pk_bf16_f32 v96, v149, v153
	v_cvt_pk_bf16_f32 v97, v157, v161
	v_cvt_pk_bf16_f32 v98, v165, v169
	v_cvt_pk_bf16_f32 v99, v173, v177
	v_cvt_pk_bf16_f32 v100, v118, v122
	v_cvt_pk_bf16_f32 v101, v126, v130
	v_cvt_pk_bf16_f32 v102, v134, v138
	v_cvt_pk_bf16_f32 v103, v142, v146
	v_cvt_pk_bf16_f32 v104, v150, v154
	v_cvt_pk_bf16_f32 v105, v158, v162
	v_cvt_pk_bf16_f32 v106, v166, v170
	v_cvt_pk_bf16_f32 v107, v174, v178
	v_cvt_pk_bf16_f32 v108, v119, v123
	v_cvt_pk_bf16_f32 v109, v127, v131
	v_cvt_pk_bf16_f32 v110, v135, v139
	v_cvt_pk_bf16_f32 v111, v143, v147
	v_cvt_pk_bf16_f32 v112, v151, v155
	v_cvt_pk_bf16_f32 v113, v159, v163
	v_cvt_pk_bf16_f32 v114, v167, v171
	v_cvt_pk_bf16_f32 v115, v175, v179
	global_store_dwordx4 v11, v[84:87], s[20:21] offset:-4096
	global_store_dwordx4 v11, v[88:91], s[20:21] offset:-4080
	global_store_dwordx4 v11, v[92:95], s[20:21] offset:-2048
	global_store_dwordx4 v11, v[96:99], s[20:21] offset:-2032
	global_store_dwordx4 v11, v[100:103], s[20:21]
	global_store_dwordx4 v11, v[104:107], s[20:21] offset:16
	global_store_dwordx4 v11, v[108:111], s[20:21] offset:2048
	global_store_dwordx4 v11, v[112:115], s[20:21] offset:2064
	s_waitcnt vmcnt(0)
	v_cvt_pk_bf16_f32 v84, v20, v24
	v_cvt_pk_bf16_f32 v85, v28, v32
	v_cvt_pk_bf16_f32 v86, v36, v40
	v_cvt_pk_bf16_f32 v87, v44, v48
	v_cvt_pk_bf16_f32 v88, v52, v56
	v_cvt_pk_bf16_f32 v89, v60, v64
	v_cvt_pk_bf16_f32 v90, v68, v72
	v_cvt_pk_bf16_f32 v91, v76, v80
	v_cvt_pk_bf16_f32 v92, v21, v25
	v_cvt_pk_bf16_f32 v93, v29, v33
	v_cvt_pk_bf16_f32 v94, v37, v41
	v_cvt_pk_bf16_f32 v95, v45, v49
	v_cvt_pk_bf16_f32 v96, v53, v57
	v_cvt_pk_bf16_f32 v97, v61, v65
	v_cvt_pk_bf16_f32 v98, v69, v73
	v_cvt_pk_bf16_f32 v99, v77, v81
	v_cvt_pk_bf16_f32 v100, v22, v26
	v_cvt_pk_bf16_f32 v101, v30, v34
	v_cvt_pk_bf16_f32 v102, v38, v42
	v_cvt_pk_bf16_f32 v103, v46, v50
	v_cvt_pk_bf16_f32 v104, v54, v58
	v_cvt_pk_bf16_f32 v105, v62, v66
	v_cvt_pk_bf16_f32 v106, v70, v74
	v_cvt_pk_bf16_f32 v107, v78, v82
	v_cvt_pk_bf16_f32 v108, v23, v27
	v_cvt_pk_bf16_f32 v109, v31, v35
	v_cvt_pk_bf16_f32 v110, v39, v43
	v_cvt_pk_bf16_f32 v111, v47, v51
	v_cvt_pk_bf16_f32 v112, v55, v59
	v_cvt_pk_bf16_f32 v113, v63, v67
	v_cvt_pk_bf16_f32 v114, v71, v75
	v_cvt_pk_bf16_f32 v115, v79, v83
	global_store_dwordx4 v11, v[84:87], s[30:31] offset:-4096
	global_store_dwordx4 v11, v[88:91], s[30:31] offset:-4080
	global_store_dwordx4 v11, v[92:95], s[30:31] offset:-2048
	global_store_dwordx4 v11, v[96:99], s[30:31] offset:-2032
	global_store_dwordx4 v11, v[100:103], s[30:31]
	global_store_dwordx4 v11, v[104:107], s[30:31] offset:16
	global_store_dwordx4 v11, v[108:111], s[30:31] offset:2048
	global_store_dwordx4 v11, v[112:115], s[30:31] offset:2064
